# v75 stack + nt on the P4 gate loads and the P5 x residual loads (read-once streams kept out of the memory-side cache)
# baseline (speedup 1.0000x reference)
.LBB0_947:
	s_lshl_b32 s15, s40, 8
	v_mov_b32_e32 v82, v237
	v_mov_b32_e32 v83, v238
	s_add_i32 s15, s15, s44
	s_lshl_b32 s0, s0, 8
	s_or_b32 s0, s0, s45
	v_add_u32_e32 v228, s15, v82
	v_lshl_add_u32 v218, v83, 3, s0
	s_cmp_eq_u32 s1, 0
	v_ashrrev_i32_e32 v229, 31, v228
	v_ashrrev_i32_e32 v219, 31, v218
	s_cselect_b64 s[40:41], -1, 0
	s_cmp_lg_u32 s1, 0
	v_lshlrev_b64 v[82:83], 10, v[228:229]
	s_cselect_b64 s[28:29], -1, 0
	v_lshl_add_u64 v[82:83], v[82:83], 0, v[218:219]
	s_mov_b64 s[0:1], -1
	s_and_b64 vcc, exec, s[40:41]
	s_cbranch_vccnz .LBB0_949
	v_lshl_add_u64 v[84:85], v[82:83], 1, s[68:69]
	global_load_dwordx4 v[162:165], v[84:85], off nt
	s_mov_b64 s[0:1], 0
.LBB0_949:
	s_andn2_b64 vcc, exec, s[0:1]
	s_cbranch_vccnz .LBB0_951
	v_lshl_add_u64 v[84:85], v[82:83], 1, s[8:9]
	global_load_dwordx4 v[150:153], v[84:85], off nt
.LBB0_951:
	v_cndmask_b32_e64 v84, 0, 1, s[28:29]
	v_lshl_add_u64 v[82:83], v[82:83], 0, s[10:11]
	v_cmp_ne_u32_e64 s[0:1], 1, v84
	s_andn2_b64 vcc, exec, s[28:29]
	s_mov_b64 s[28:29], -1
	s_cbranch_vccnz .LBB0_953
	v_lshl_add_u64 v[84:85], v[82:83], 1, s[68:69]
	global_load_dwordx4 v[166:169], v[84:85], off nt
	s_mov_b64 s[28:29], 0
.LBB0_953:
	s_andn2_b64 vcc, exec, s[28:29]
	s_cbranch_vccnz .LBB0_955
	v_lshl_add_u64 v[82:83], v[82:83], 1, s[8:9]
	global_load_dwordx4 v[138:141], v[82:83], off nt
.LBB0_955:
	v_add_u32_e32 v210, 16, v228
	v_ashrrev_i32_e32 v211, 31, v210
	v_lshlrev_b64 v[82:83], 10, v[210:211]
	v_lshl_add_u64 v[82:83], v[82:83], 0, v[218:219]
	s_and_b64 vcc, exec, s[0:1]
	s_mov_b64 s[28:29], -1
	s_cbranch_vccnz .LBB0_957
	v_lshl_add_u64 v[84:85], v[82:83], 1, s[68:69]
	global_load_dwordx4 v[170:173], v[84:85], off nt
	s_cbranch_execnz .LBB0_959
	s_branch .LBB0_958

.LBB0_958:
	v_lshl_add_u64 v[84:85], v[82:83], 1, s[8:9]
	global_load_dwordx4 v[126:129], v[84:85], off nt
.LBB0_959:
	v_lshl_add_u64 v[82:83], v[82:83], 0, s[10:11]
	s_and_b64 vcc, exec, s[0:1]
	s_mov_b64 s[28:29], -1
	s_cbranch_vccnz .LBB0_961
	v_lshl_add_u64 v[84:85], v[82:83], 1, s[68:69]
	global_load_dwordx4 v[174:177], v[84:85], off nt
	s_cbranch_execz .LBB0_962
	s_branch .LBB0_963

.LBB0_962:
	v_lshl_add_u64 v[82:83], v[82:83], 1, s[8:9]
	global_load_dwordx4 v[122:125], v[82:83], off nt
.LBB0_963:
	v_add_u32_e32 v220, 32, v228
	v_ashrrev_i32_e32 v221, 31, v220
	v_lshlrev_b64 v[82:83], 10, v[220:221]
	v_lshl_add_u64 v[82:83], v[82:83], 0, v[218:219]
	s_and_b64 vcc, exec, s[0:1]
	s_mov_b64 s[28:29], -1
	s_cbranch_vccnz .LBB0_965
	v_lshl_add_u64 v[84:85], v[82:83], 1, s[68:69]
	global_load_dwordx4 v[178:181], v[84:85], off nt
	s_cbranch_execnz .LBB0_967
	s_branch .LBB0_966

.LBB0_966:
	v_lshl_add_u64 v[84:85], v[82:83], 1, s[8:9]
	global_load_dwordx4 v[110:113], v[84:85], off nt
.LBB0_967:
	v_lshl_add_u64 v[82:83], v[82:83], 0, s[10:11]
	s_and_b64 vcc, exec, s[0:1]
	s_mov_b64 s[28:29], -1
	s_cbranch_vccnz .LBB0_969
	v_lshl_add_u64 v[84:85], v[82:83], 1, s[68:69]
	global_load_dwordx4 v[182:185], v[84:85], off nt
	s_cbranch_execz .LBB0_970
	s_branch .LBB0_971

.LBB0_970:
	v_lshl_add_u64 v[82:83], v[82:83], 1, s[8:9]
	global_load_dwordx4 v[98:101], v[82:83], off nt
.LBB0_971:
	v_add_u32_e32 v230, 48, v228
	v_ashrrev_i32_e32 v231, 31, v230
	v_lshlrev_b64 v[82:83], 10, v[230:231]
	v_lshl_add_u64 v[82:83], v[82:83], 0, v[218:219]
	s_and_b64 vcc, exec, s[0:1]
	s_mov_b64 s[28:29], -1
	s_cbranch_vccnz .LBB0_973
	v_lshl_add_u64 v[84:85], v[82:83], 1, s[68:69]
	global_load_dwordx4 v[186:189], v[84:85], off nt
	s_cbranch_execnz .LBB0_975
	s_branch .LBB0_974

.LBB0_974:
	v_lshl_add_u64 v[84:85], v[82:83], 1, s[8:9]
	global_load_dwordx4 v[94:97], v[84:85], off nt
.LBB0_975:
	v_lshl_add_u64 v[194:195], v[82:83], 0, s[10:11]
	s_and_b64 vcc, exec, s[0:1]
	s_mov_b64 s[28:29], -1
	s_cbranch_vccnz .LBB0_977
	v_lshl_add_u64 v[82:83], v[194:195], 1, s[68:69]
	global_load_dwordx4 v[190:193], v[82:83], off nt
	s_cbranch_execz .LBB0_978
	s_branch .LBB0_979

.LBB0_978:
	v_lshl_add_u64 v[82:83], v[194:195], 1, s[8:9]
	global_load_dwordx4 v[82:85], v[82:83], off nt

.LBB0_1011:
	v_add_u32_e32 v232, 0x80, v228
	v_ashrrev_i32_e32 v233, 31, v232
	v_lshlrev_b64 v[66:67], 10, v[232:233]
	v_lshl_add_u64 v[66:67], v[66:67], 0, v[218:219]
	s_and_b64 vcc, exec, s[0:1]
	s_mov_b64 s[28:29], -1
	s_cbranch_vccnz .LBB0_1013
	v_lshl_add_u64 v[68:69], v[66:67], 1, s[68:69]
	global_load_dwordx4 v[106:109], v[68:69], off nt
	s_cbranch_execnz .LBB0_1015
	s_branch .LBB0_1014

.LBB0_1014:
	v_lshl_add_u64 v[68:69], v[66:67], 1, s[8:9]
	global_load_dwordx4 v[150:153], v[68:69], off nt
	s_waitcnt vmcnt(1)
	v_mov_b64_e32 v[106:107], v[162:163]
	v_mov_b64_e32 v[108:109], v[164:165]
.LBB0_1015:
	v_lshl_add_u64 v[66:67], v[66:67], 0, s[10:11]
	s_and_b64 vcc, exec, s[0:1]
	s_mov_b64 s[28:29], -1
	s_cbranch_vccnz .LBB0_1017
	v_lshl_add_u64 v[68:69], v[66:67], 1, s[68:69]
	global_load_dwordx4 v[102:105], v[68:69], off nt
	s_cbranch_execz .LBB0_1018
	s_branch .LBB0_1019

.LBB0_1018:
	v_lshl_add_u64 v[66:67], v[66:67], 1, s[8:9]
	global_load_dwordx4 v[138:141], v[66:67], off nt
	s_waitcnt vmcnt(1)
	v_mov_b64_e32 v[102:103], v[166:167]
	v_mov_b64_e32 v[104:105], v[168:169]
.LBB0_1019:
	v_add_u32_e32 v230, 0x90, v228
	v_ashrrev_i32_e32 v231, 31, v230
	v_lshlrev_b64 v[66:67], 10, v[230:231]
	v_lshl_add_u64 v[66:67], v[66:67], 0, v[218:219]
	s_and_b64 vcc, exec, s[0:1]
	s_mov_b64 s[28:29], -1
	s_cbranch_vccnz .LBB0_1021
	v_lshl_add_u64 v[68:69], v[66:67], 1, s[68:69]
	global_load_dwordx4 v[90:93], v[68:69], off nt
	s_cbranch_execnz .LBB0_1023
	s_branch .LBB0_1022

.LBB0_1022:
	v_lshl_add_u64 v[68:69], v[66:67], 1, s[8:9]
	global_load_dwordx4 v[126:129], v[68:69], off nt
	s_waitcnt vmcnt(1)
	v_mov_b64_e32 v[90:91], v[170:171]
	v_mov_b64_e32 v[92:93], v[172:173]
.LBB0_1023:
	v_lshl_add_u64 v[66:67], v[66:67], 0, s[10:11]
	s_and_b64 vcc, exec, s[0:1]
	s_mov_b64 s[28:29], -1
	s_cbranch_vccnz .LBB0_1025
	v_lshl_add_u64 v[68:69], v[66:67], 1, s[68:69]
	global_load_dwordx4 v[86:89], v[68:69], off nt
	s_cbranch_execz .LBB0_1026
	s_branch .LBB0_1027

.LBB0_1026:
	v_lshl_add_u64 v[66:67], v[66:67], 1, s[8:9]
	global_load_dwordx4 v[122:125], v[66:67], off nt
	s_waitcnt vmcnt(1)
	v_mov_b64_e32 v[86:87], v[174:175]
	v_mov_b64_e32 v[88:89], v[176:177]
.LBB0_1027:
	s_waitcnt vmcnt(0)
	v_add_u32_e32 v172, 0xa0, v228
	v_ashrrev_i32_e32 v173, 31, v172
	v_lshlrev_b64 v[66:67], 10, v[172:173]
	v_lshl_add_u64 v[66:67], v[66:67], 0, v[218:219]
	s_and_b64 vcc, exec, s[0:1]
	s_mov_b64 s[28:29], -1
	s_cbranch_vccnz .LBB0_1029
	v_lshl_add_u64 v[68:69], v[66:67], 1, s[68:69]
	global_load_dwordx4 v[78:81], v[68:69], off nt
	s_cbranch_execnz .LBB0_1031
	s_branch .LBB0_1030

.LBB0_1030:
	v_lshl_add_u64 v[68:69], v[66:67], 1, s[8:9]
	global_load_dwordx4 v[110:113], v[68:69], off nt
	s_waitcnt vmcnt(1)
	v_mov_b64_e32 v[78:79], v[178:179]
	v_mov_b64_e32 v[80:81], v[180:181]
.LBB0_1031:
	v_lshl_add_u64 v[66:67], v[66:67], 0, s[10:11]
	s_and_b64 vcc, exec, s[0:1]
	s_mov_b64 s[28:29], -1
	s_cbranch_vccnz .LBB0_1033
	v_lshl_add_u64 v[68:69], v[66:67], 1, s[68:69]
	global_load_dwordx4 v[74:77], v[68:69], off nt
	s_cbranch_execz .LBB0_1034
	s_branch .LBB0_1035

.LBB0_1034:
	v_lshl_add_u64 v[66:67], v[66:67], 1, s[8:9]
	global_load_dwordx4 v[98:101], v[66:67], off nt
	s_waitcnt vmcnt(1)
	v_mov_b64_e32 v[74:75], v[182:183]
	v_mov_b64_e32 v[76:77], v[184:185]
.LBB0_1035:
	v_add_u32_e32 v170, 0xb0, v228
	v_ashrrev_i32_e32 v171, 31, v170
	v_lshlrev_b64 v[66:67], 10, v[170:171]
	v_lshl_add_u64 v[66:67], v[66:67], 0, v[218:219]
	s_and_b64 vcc, exec, s[0:1]
	s_mov_b64 s[28:29], -1
	s_cbranch_vccnz .LBB0_1037
	v_lshl_add_u64 v[68:69], v[66:67], 1, s[68:69]
	global_load_dwordx4 v[70:73], v[68:69], off nt
	s_cbranch_execnz .LBB0_1039
	s_branch .LBB0_1038

.LBB0_1038:
	v_lshl_add_u64 v[68:69], v[66:67], 1, s[8:9]
	global_load_dwordx4 v[94:97], v[68:69], off nt
	s_waitcnt vmcnt(1)
	v_mov_b64_e32 v[70:71], v[186:187]
	v_mov_b64_e32 v[72:73], v[188:189]
.LBB0_1039:
	v_lshl_add_u64 v[162:163], v[66:67], 0, s[10:11]
	s_and_b64 vcc, exec, s[0:1]
	s_mov_b64 s[28:29], -1
	s_cbranch_vccnz .LBB0_1041
	v_lshl_add_u64 v[66:67], v[162:163], 1, s[68:69]
	global_load_dwordx4 v[66:69], v[66:67], off nt
	s_cbranch_execz .LBB0_1042
	s_branch .LBB0_1043

.LBB0_1042:
	s_waitcnt vmcnt(0)
	v_lshl_add_u64 v[66:67], v[162:163], 1, s[8:9]
	global_load_dwordx4 v[82:85], v[66:67], off nt
	v_mov_b64_e32 v[66:67], v[190:191]
	v_mov_b64_e32 v[68:69], v[192:193]

.LBB0_1155:
	s_lshl_b32 s0, s28, 8
	s_add_i32 s17, s0, s50
	s_lshl_b32 s0, s8, 8
	v_mov_b32_e32 v217, v210
	v_mov_b32_e32 v148, v209
	s_or_b32 s0, s0, s51
	v_readlane_b32 s64, v253, 4
	v_lshl_add_u32 v194, v217, 3, s0
	s_ashr_i32 s0, s28, 5
	s_mul_hi_i32 s1, s0, 0x6000
	s_mulk_i32 s0, 0x6000
	s_add_u32 s0, s92, s0
	v_ashrrev_i32_e32 v195, 31, v194
	s_addc_u32 s1, s93, s1
	v_lshlrev_b64 v[146:147], 2, v[194:195]
	v_lshl_add_u64 v[50:51], s[0:1], 0, v[146:147]
	v_add_u32_e32 v196, s17, v148
	v_lshl_add_u64 v[54:55], v[50:51], 0, s[14:15]
	v_add_co_u32_e32 v50, vcc, s3, v50
	v_readlane_b32 s65, v253, 5
	v_ashrrev_i32_e32 v197, 31, v196
	v_addc_co_u32_e32 v51, vcc, 0, v51, vcc
	v_lshl_add_u64 v[198:199], s[64:65], 0, v[146:147]
	v_lshlrev_b64 v[146:147], 12, v[196:197]
	global_load_dwordx4 v[62:65], v[50:51], off
	s_nop 0
	global_load_dwordx4 v[50:53], v[54:55], off offset:528
	global_load_dwordx4 v[58:61], v[54:55], off offset:16
	s_nop 0
	global_load_dwordx4 v[54:57], v[54:55], off offset:512
	v_lshl_add_u64 v[146:147], v[198:199], 0, v[146:147]
	global_load_dwordx4 v[218:221], v[146:147], off nt
	global_load_dwordx4 v[222:225], v[146:147], off offset:16 nt
	global_load_dwordx4 v[226:229], v[146:147], off offset:512 nt
	global_load_dwordx4 v[230:233], v[146:147], off offset:528 nt
	v_add_u32_e32 v204, 16, v196
	v_add_u32_e32 v202, 32, v196
	v_add_u32_e32 v200, 48, v196
	v_ashrrev_i32_e32 v205, 31, v204
	v_ashrrev_i32_e32 v203, 31, v202
	v_ashrrev_i32_e32 v201, 31, v200
	v_lshlrev_b64 v[146:147], 12, v[204:205]
	v_lshlrev_b64 v[148:149], 12, v[202:203]
	v_lshlrev_b64 v[150:151], 12, v[200:201]
	v_lshl_add_u64 v[146:147], v[198:199], 0, v[146:147]
	v_lshl_add_u64 v[148:149], v[198:199], 0, v[148:149]
	v_lshl_add_u64 v[150:151], v[198:199], 0, v[150:151]
	global_load_dwordx4 v[186:189], v[146:147], off offset:16 nt
	global_load_dwordx4 v[190:193], v[146:147], off nt
	global_load_dwordx4 v[178:181], v[146:147], off offset:528 nt
	global_load_dwordx4 v[182:185], v[146:147], off offset:512 nt
	global_load_dwordx4 v[170:173], v[148:149], off offset:16 nt
	global_load_dwordx4 v[174:177], v[148:149], off nt
	global_load_dwordx4 v[162:165], v[148:149], off offset:528 nt
	global_load_dwordx4 v[166:169], v[148:149], off offset:512 nt
	global_load_dwordx4 v[154:157], v[150:151], off offset:16 nt
	global_load_dwordx4 v[158:161], v[150:151], off nt
	s_nop 0
	global_load_dwordx4 v[146:149], v[150:151], off offset:528 nt
	s_nop 0
	global_load_dwordx4 v[150:153], v[150:151], off offset:512 nt
	v_cmp_eq_u32_e32 vcc, 0, v217
	v_lshlrev_b64 v[234:235], 11, v[196:197]
	v_lshl_add_u64 v[234:235], s[26:27], 0, v[234:235]
	v_lshl_add_u64 v[234:235], v[194:195], 1, v[234:235]
	s_lshl_b32 s28, s8, 2
	s_ashr_i32 s29, s28, 31
	v_readlane_b32 s66, v253, 6
	v_readlane_b32 s67, v253, 7
	v_readlane_b32 s68, v253, 8
	v_readlane_b32 s69, v253, 9
	v_readlane_b32 s70, v253, 10
	v_readlane_b32 s71, v253, 11
	v_readlane_b32 s72, v253, 12
	v_readlane_b32 s73, v253, 13
	v_readlane_b32 s74, v253, 14
	v_readlane_b32 s75, v253, 15
	v_readlane_b32 s76, v253, 16
	v_readlane_b32 s77, v253, 17
	v_readlane_b32 s78, v253, 18
	v_readlane_b32 s79, v253, 19
	s_waitcnt vmcnt(15)
	v_pk_fma_f32 v[144:145], v[144:145], v[64:65], v[220:221]
	v_pk_fma_f32 v[142:143], v[142:143], v[62:63], v[218:219]
	s_waitcnt vmcnt(14)
	v_pk_fma_f32 v[140:141], v[140:141], v[60:61], v[224:225]
	v_pk_fma_f32 v[218:219], v[138:139], v[58:59], v[222:223]
	s_waitcnt vmcnt(12)
	v_pk_fma_f32 v[220:221], v[132:133], v[52:53], v[232:233]
	v_mul_f32_e32 v132, v143, v143
	v_mul_f32_e32 v133, v145, v145
	v_mul_f32_e32 v138, v219, v219
	v_mul_f32_e32 v139, v141, v141
	v_fmac_f32_e32 v132, v142, v142
	v_fmac_f32_e32 v133, v144, v144
	v_fmac_f32_e32 v138, v218, v218
	v_fmac_f32_e32 v139, v140, v140
	v_pk_fma_f32 v[136:137], v[136:137], v[56:57], v[228:229]
	v_pk_fma_f32 v[134:135], v[134:135], v[54:55], v[226:227]
	v_pk_fma_f32 v[222:223], v[130:131], v[50:51], v[230:231]
	v_add_f32_e32 v132, v132, v133
	v_add_f32_e32 v133, v138, v139
	v_cvt_pk_bf16_f32 v130, v142, v143
	v_cvt_pk_bf16_f32 v131, v144, v145
	v_mul_f32_e32 v143, v135, v135
	v_mul_f32_e32 v145, v137, v137
	v_mul_f32_e32 v217, v223, v223
	v_add_f32_e32 v132, v132, v133
	v_mul_f32_e32 v133, v221, v221
	v_fmac_f32_e32 v143, v134, v134
	v_fmac_f32_e32 v145, v136, v136
	v_fmac_f32_e32 v217, v222, v222
	v_fmac_f32_e32 v133, v220, v220
	v_add_f32_e32 v138, v143, v145
	v_add_f32_e32 v133, v217, v133
	v_add_f32_e32 v133, v138, v133
	v_add_f32_e32 v139, v132, v133
	v_and_b32_e32 v133, 64, v216
	v_xor_b32_e32 v132, 16, v216
	v_add_u32_e32 v142, 64, v133
	v_cmp_lt_i32_e64 s[0:1], v132, v142
	s_nop 1
	v_cndmask_b32_e64 v132, v216, v132, s[0:1]
	v_lshlrev_b32_e32 v138, 2, v132
	ds_bpermute_b32 v143, v138, v139
	v_cvt_pk_bf16_f32 v132, v218, v219
	v_cvt_pk_bf16_f32 v133, v140, v141
	global_store_dwordx4 v[234:235], v[130:133], off
	s_nop 1
	v_xor_b32_e32 v131, 32, v216
	v_cmp_lt_i32_e64 s[0:1], v131, v142
	s_waitcnt lgkmcnt(0)
	v_add_f32_e32 v130, v139, v143
	v_cvt_pk_bf16_f32 v132, v134, v135
	v_cvt_pk_bf16_f32 v133, v136, v137
	v_cvt_pk_bf16_f32 v134, v222, v223
	v_cvt_pk_bf16_f32 v135, v220, v221
	v_cndmask_b32_e64 v131, v216, v131, s[0:1]
	v_lshlrev_b32_e32 v139, 2, v131
	ds_bpermute_b32 v131, v139, v130
	global_store_dwordx4 v[234:235], v[132:135], off offset:256
	s_and_saveexec_b64 s[0:1], vcc
	s_cbranch_execz .LBB0_1157
	v_lshlrev_b64 v[132:133], 6, v[196:197]
	v_lshl_add_u64 v[132:133], s[4:5], 0, v[132:133]
	v_lshl_add_u64 v[132:133], s[28:29], 2, v[132:133]
	s_lshl_b32 s8, s49, 2
	v_lshl_add_u64 v[132:133], v[132:133], 0, s[8:9]
	s_waitcnt lgkmcnt(0)
	v_add_f32_e32 v130, v130, v131
	global_store_dword v[132:133], v130, off

.LBB0_1163:
	s_or_b64 exec, exec, s[0:1]
	v_add_u32_e32 v136, 0x80, v196
	v_ashrrev_i32_e32 v137, 31, v136
	s_waitcnt lgkmcnt(0)
	v_lshlrev_b64 v[82:83], 12, v[136:137]
	v_lshl_add_u64 v[82:83], v[198:199], 0, v[82:83]
	global_load_dwordx4 v[140:143], v[82:83], off nt
	global_load_dwordx4 v[144:147], v[82:83], off offset:16 nt
	global_load_dwordx4 v[148:151], v[82:83], off offset:512 nt
	global_load_dwordx4 v[152:155], v[82:83], off offset:528 nt
	v_add_u32_e32 v134, 0x90, v196
	v_add_u32_e32 v132, 0xa0, v196
	v_add_u32_e32 v130, 0xb0, v196
	v_ashrrev_i32_e32 v135, 31, v134
	v_ashrrev_i32_e32 v133, 31, v132
	v_ashrrev_i32_e32 v131, 31, v130
	v_lshlrev_b64 v[82:83], 12, v[134:135]
	v_lshlrev_b64 v[84:85], 12, v[132:133]
	v_lshlrev_b64 v[86:87], 12, v[130:131]
	v_lshl_add_u64 v[82:83], v[198:199], 0, v[82:83]
	v_lshl_add_u64 v[84:85], v[198:199], 0, v[84:85]
	v_lshl_add_u64 v[86:87], v[198:199], 0, v[86:87]
	global_load_dwordx4 v[122:125], v[82:83], off offset:16 nt
	global_load_dwordx4 v[126:129], v[82:83], off nt
	global_load_dwordx4 v[114:117], v[82:83], off offset:528 nt
	global_load_dwordx4 v[118:121], v[82:83], off offset:512 nt
	global_load_dwordx4 v[106:109], v[84:85], off offset:16 nt
	global_load_dwordx4 v[110:113], v[84:85], off nt
	global_load_dwordx4 v[98:101], v[84:85], off offset:528 nt
	global_load_dwordx4 v[102:105], v[84:85], off offset:512 nt
	global_load_dwordx4 v[90:93], v[86:87], off offset:16 nt
	global_load_dwordx4 v[94:97], v[86:87], off nt
	s_nop 0
	global_load_dwordx4 v[82:85], v[86:87], off offset:528 nt
	s_nop 0
	global_load_dwordx4 v[86:89], v[86:87], off offset:512 nt
	v_lshlrev_b64 v[156:157], 11, v[136:137]
	v_lshl_add_u64 v[156:157], s[26:27], 0, v[156:157]
	v_lshl_add_u64 v[156:157], v[194:195], 1, v[156:157]
	s_waitcnt vmcnt(15)
	v_pk_fma_f32 v[80:81], v[80:81], v[64:65], v[142:143]
	v_pk_fma_f32 v[78:79], v[78:79], v[62:63], v[140:141]
	s_waitcnt vmcnt(14)
	v_pk_fma_f32 v[76:77], v[76:77], v[60:61], v[146:147]
	v_pk_fma_f32 v[74:75], v[74:75], v[58:59], v[144:145]
	s_waitcnt vmcnt(13)
	v_pk_fma_f32 v[72:73], v[72:73], v[56:57], v[150:151]
	v_pk_fma_f32 v[70:71], v[70:71], v[54:55], v[148:149]
	s_waitcnt vmcnt(12)
	v_pk_fma_f32 v[140:141], v[68:69], v[52:53], v[154:155]
	v_pk_fma_f32 v[142:143], v[66:67], v[50:51], v[152:153]
	v_mul_f32_e32 v68, v79, v79
	v_mul_f32_e32 v69, v81, v81
	v_mul_f32_e32 v144, v75, v75
	v_mul_f32_e32 v145, v77, v77
	v_cvt_pk_bf16_f32 v66, v78, v79
	v_cvt_pk_bf16_f32 v67, v80, v81
	v_mul_f32_e32 v79, v71, v71
	v_mul_f32_e32 v81, v73, v73
	v_mul_f32_e32 v146, v143, v143
	v_mul_f32_e32 v147, v141, v141
	v_fmac_f32_e32 v68, v78, v78
	v_fmac_f32_e32 v69, v80, v80
	v_fmac_f32_e32 v144, v74, v74
	v_fmac_f32_e32 v145, v76, v76
	v_fmac_f32_e32 v79, v70, v70
	v_fmac_f32_e32 v81, v72, v72
	v_fmac_f32_e32 v146, v142, v142
	v_fmac_f32_e32 v147, v140, v140
	v_add_f32_e32 v68, v68, v69
	v_add_f32_e32 v69, v144, v145
	v_add_f32_e32 v78, v79, v81
	v_add_f32_e32 v79, v146, v147
	v_add_f32_e32 v68, v68, v69
	v_add_f32_e32 v69, v78, v79
	v_add_f32_e32 v78, v68, v69
	ds_bpermute_b32 v79, v138, v78
	v_cvt_pk_bf16_f32 v68, v74, v75
	v_cvt_pk_bf16_f32 v69, v76, v77
	global_store_dwordx4 v[156:157], v[66:69], off
	s_waitcnt lgkmcnt(0)
	s_nop 0
	v_add_f32_e32 v66, v78, v79
	ds_bpermute_b32 v67, v139, v66
	v_cvt_pk_bf16_f32 v68, v70, v71
	v_cvt_pk_bf16_f32 v69, v72, v73
	v_cvt_pk_bf16_f32 v70, v142, v143
	v_cvt_pk_bf16_f32 v71, v140, v141
	global_store_dwordx4 v[156:157], v[68:71], off offset:256
	s_and_saveexec_b64 s[0:1], vcc
	s_cbranch_execz .LBB0_1165
	v_lshlrev_b64 v[68:69], 6, v[136:137]
	v_lshl_add_u64 v[68:69], s[4:5], 0, v[68:69]
	v_lshl_add_u64 v[68:69], s[28:29], 2, v[68:69]
	s_lshl_b32 s8, s49, 2
	v_lshl_add_u64 v[68:69], v[68:69], 0, s[8:9]
	s_waitcnt lgkmcnt(0)
	v_add_f32_e32 v66, v66, v67
	global_store_dword v[68:69], v66, off
